# FFN-up under-filled last round on XCDs 0-3 only; workgroups on XCDs 4-7 convert 4 tiles each
# speedup vs baseline: 1.0045x; 1.0045x over previous
; __global__ void __launch_bounds__(NWAVES * 64, 2) mega_fwd(Args A) {
;     ...
;     for (int step = 0; step < 3 * DEPTH; ++step) {
;         const int l = step / 3, kind = step - 3 * l;
;         unsigned char* wl = ws + WS_W + (size_t)l * LW_END;
;         const unsigned long long* ssq = (const unsigned long long*)(ws + WS_CTL + CTL_SSQ) + (size_t)step * NTOK; unsigned long long* ssq_next = (unsigned long long*)(ws + WS_CTL + CTL_SSQ) + (size_t)(step + 1) * NTOK;
;         if (kind != 1) {
;             { pg8::Gemm g{H, (const bf16*)(wl + (kind == 0 ? LW_WI1 : LW_WI2)), NTOK, NWI, DM}; pg8::StaticOrder S; S.init(NTOK, NWI, G, bx);
;               pg8::EpiSwiglu E{ACT, DFF, ssq};
;               pg8::gemm_phase<pg8::EpiSwiglu, pg8::StaticOrder, true, true>(lds + RING_OFF, g, S, E); }
;             { const int rem1 = ((NTOK / 256) * (NWI / 256)) % G;
;               conv_until(A, lds, l * TL_LAYER + (kind == 0 ? TL_WIN : TL_LAYER), (rem1 != 0 && bx >= rem1) ? 3 : 0); }
;             xcd_barrier(bar);
;         } else {
;             const bool std256 = (G == 256);
;             unsigned char* XB8 = ws + WS_X;
; #pragma unroll 1
;             for (int part = 0; part < 3; ++part) {
;                 bool do16, do8; int i16, n16, g8, c8, i8, n8;
;                 if (std256) { do16 = part == 0 || (part == 1 && bx < 64); i16 = part ? 2 : 0; n16 = part ? 1 : 2;
;                               do8 = (part == 1 && bx >= 64) || (part == 2 && bx < 128); g8 = part == 1 ? 192 : 128; c8 = part == 1 ? bx - 64 : bx; i8 = part == 1 ? 0 : 3; n8 = part == 1 ? 2 : 3; }
;                 else { do16 = part == 0; i16 = 0; n16 = 1 << 20; do8 = part == 1; g8 = G; c8 = bx; i8 = 0; n8 = 1 << 20; }
;                 if (do16) { pg8::Gemm g{H, (const bf16*)(wl + LW_WIN), NTOK, C_GATE, DM}; pg8::RangeOrder S; S.init(NTOK, C_GATE, G, bx); S.i0 = i16; S.n = n16;
;                     pg8::EpiProj E{PROJ, NPROJ, (const float*)A.in[7] + (size_t)l * 6144, 1 << 20, ssq, 1.0f};
;                     pg8::gemm_phase<pg8::EpiProj, pg8::RangeOrder, true, true>(lds + RING_OFF, g, S, E); }
;                 if (do8) { pg8::Gemm g{(const bf16*)XB8, (const bf16*)(wl + LW_WIN + WIN8_OFF), NTOK, 6144, DM / 2}; pg8::RangeOrder S; S.init(NTOK, 6144, g8, c8); S.i0 = i8; S.n = n8;
.LBB0_284:
	v_writelane_b32 v252, s64, 42
	s_nop 1
	v_writelane_b32 v252, s65, 43
	v_writelane_b32 v252, s66, 44
	v_writelane_b32 v252, s67, 45
	v_writelane_b32 v252, s68, 46
	v_writelane_b32 v252, s69, 47
	v_writelane_b32 v252, s70, 48
	v_writelane_b32 v252, s71, 49
	v_writelane_b32 v252, s72, 50
	v_writelane_b32 v252, s73, 51
	v_writelane_b32 v252, s74, 52
	v_writelane_b32 v252, s75, 53
	v_writelane_b32 v252, s76, 54
	v_writelane_b32 v252, s77, 55
	v_writelane_b32 v252, s78, 56
	v_writelane_b32 v252, s79, 57
	s_or_b64 exec, exec, s[0:1]
	s_cmpk_lg_i32 s95, 0x100
	s_cselect_b64 s[0:1], -1, 0
	s_and_b64 s[0:1], s[0:1], exec
	s_cselect_b32 s69, s95, 0x80
	s_add_i32 s4, s97, 0xffffff80
	s_cmpk_lg_i32 s95, 0x100
	s_cselect_b64 s[0:1], -1, 0
	s_and_b64 s[2:3], s[0:1], exec
	s_cselect_b32 s20, s97, s4
	v_readlane_b32 s4, v252, 2
	v_readlane_b32 s18, v252, 16
	v_readlane_b32 s19, v252, 17
	s_add_u32 s74, s18, 0x10000
	s_addc_u32 s2, s19, 0
	v_readlane_b32 s5, v252, 3
	v_readlane_b32 s6, v252, 4
	v_readlane_b32 s7, v252, 5
	v_readlane_b32 s8, v252, 6
	v_readlane_b32 s9, v252, 7
	v_readlane_b32 s10, v252, 8
	v_readlane_b32 s11, v252, 9
	v_readlane_b32 s12, v252, 10
	v_readlane_b32 s13, v252, 11
	v_readlane_b32 s14, v252, 12
	v_readlane_b32 s15, v252, 13
	v_readlane_b32 s16, v252, 14
	v_readlane_b32 s17, v252, 15
	v_writelane_b32 v252, s2, 58
	s_add_u32 s2, s18, 0x35e00000
	s_addc_u32 s3, s19, 0
	s_add_u32 s88, s18, 0x3b600000
	s_addc_u32 s89, s19, 0
	v_writelane_b32 v252, s2, 59
	s_add_u32 s12, s18, 0x45e00000
	s_addc_u32 s13, s19, 0
	v_writelane_b32 v252, s3, 60
	v_writelane_b32 v252, s12, 61
	s_add_u32 s2, s18, 0x4c200000
	v_writelane_b32 v252, s13, 62
	s_addc_u32 s3, s19, 0
	v_writelane_b32 v252, s2, 63
	s_waitcnt vmcnt(15)
	v_mov_b32_e32 v3, 0
	v_mov_b32_e32 v216, 1
	v_writelane_b32 v253, s3, 0
	s_add_u32 s2, s18, 0x4e200000
	s_addc_u32 s3, s19, 0
	v_writelane_b32 v253, s2, 1
	v_mov_b32_e32 v217, 0x7f7f7f7f
	v_mov_b32_e32 v225, 0x43e00000
	v_writelane_b32 v253, s3, 2
	s_add_u32 s2, s18, 0x4fa00000
	s_addc_u32 s3, s19, 0
	v_writelane_b32 v253, s2, 3
	v_mov_b64_e32 v[226:227], 0x2ff
	v_mov_b32_e32 v222, 0x41b17218
	v_writelane_b32 v253, s3, 4
	s_add_u32 s2, s18, 0x4fb00000
	s_addc_u32 s3, s19, 0
	v_writelane_b32 v253, s2, 5
	v_mbcnt_hi_u32_b32 v223, -1, v76
	v_mov_b32_e32 v224, 0xf149f2ca
	v_writelane_b32 v253, s3, 6
	s_add_u32 s2, s18, 0x200000
	v_writelane_b32 v253, s2, 7
	s_addc_u32 s2, s19, 0
	s_cmpk_lt_i32 s97, 0x580
	v_writelane_b32 v253, s2, 8
	s_cselect_b64 s[2:3], -1, 0
	v_writelane_b32 v253, s2, 9
	s_ashr_i32 s21, s97, 31
	s_movk_i32 s75, 0xc0
	v_writelane_b32 v253, s3, 10
	s_lshr_b32 s2, s21, 29
	s_add_i32 s3, s97, s2
	s_ashr_i32 s2, s3, 3
	s_and_b32 s3, s3, -8
	s_sub_i32 s5, s97, s3
	s_ashr_i32 s3, s95, 31
	s_add_u32 s6, s18, 0x4200
	v_writelane_b32 v253, s3, 11
	s_addc_u32 s7, s19, 0
	v_writelane_b32 v253, s6, 12
	s_movk_i32 s76, 0x300
	s_movk_i32 s77, 0x5400
	v_writelane_b32 v253, s7, 13
	s_add_u32 s6, s18, 0x4400
	s_addc_u32 s7, s19, 0
	v_writelane_b32 v253, s6, 14
	s_movk_i32 s81, 0x7fff
	s_mov_b32 s82, 0xffff0000
	v_writelane_b32 v253, s7, 15
	s_add_u32 s6, s18, 0x4500
	s_addc_u32 s7, s19, 0
	v_writelane_b32 v253, s6, 16
	s_movk_i32 s61, 0x1110
	s_movk_i32 s84, 0x15ff
	v_writelane_b32 v253, s7, 17
	s_add_u32 s6, s18, 0x4600
	s_addc_u32 s7, s19, 0
	v_writelane_b32 v253, s6, 18
	s_mov_b32 s85, 0xc3e00000
	s_movk_i32 s33, 0xff
	v_writelane_b32 v253, s7, 19
	s_add_u32 s6, s18, 0x4700
	s_addc_u32 s7, s19, 0
	v_writelane_b32 v253, s6, 20
	s_movk_i32 s66, 0x90
	s_mov_b32 s96, 0x2aaaaaab
	v_writelane_b32 v253, s7, 21
	s_add_u32 s6, s18, 0x4800
	s_addc_u32 s7, s19, 0
	v_writelane_b32 v253, s6, 22
	s_movk_i32 s36, 0x190
	s_movk_i32 s37, 0xff40
	v_writelane_b32 v253, s7, 23
	s_add_u32 s6, s18, 0x4900
	s_addc_u32 s7, s19, 0
	v_writelane_b32 v253, s6, 24
	s_movk_i32 s38, 0x567
	s_movk_i32 s39, 0x1500
	v_writelane_b32 v253, s7, 25
	s_add_u32 s6, s18, 0x4a00
	s_addc_u32 s7, s19, 0
	v_writelane_b32 v253, s6, 26
	s_movk_i32 s56, 0x1800
	s_movk_i32 s57, 0xc80
	v_writelane_b32 v253, s7, 27
	s_add_u32 s6, s18, 0x4b00
	s_addc_u32 s7, s19, 0
	v_writelane_b32 v253, s6, 28
	s_movk_i32 s58, 0x3ff
	s_mov_b32 s80, 0xefa18f08
	v_writelane_b32 v253, s7, 29
	s_add_u32 s6, s18, 0x4c00
	s_addc_u32 s7, s19, 0
	v_writelane_b32 v253, s6, 30
	s_mov_b32 s62, 0
	s_mov_b32 s94, 0x3e000000
	v_writelane_b32 v253, s7, 31
	s_add_u32 s6, s18, 0x4d00
	s_addc_u32 s7, s19, 0
	v_writelane_b32 v253, s6, 32
	s_waitcnt lgkmcnt(0)
	s_barrier
; __global__ void __launch_bounds__(NWAVES * 64, 2) mega_fwd(Args A) {
;     ...
;                 if (std256) { do16 = part == 0 || (part == 1 && bx < 64); i16 = part ? 2 : 0; n16 = part ? 1 : 2;
;                               do8 = (part == 1 && bx >= 64) || (part == 2 && bx < 128); g8 = part == 1 ? 192 : 128; c8 = part == 1 ? bx - 64 : bx; i8 = part == 1 ? 0 : 3; n8 = part == 1 ? 2 : 3; }
;                 else { do16 = part == 0; i16 = 0; n16 = 1 << 20; do8 = part == 1; g8 = G; c8 = bx; i8 = 0; n8 = 1 << 20; }
;                 if (do16) { pg8::Gemm g{H, (const bf16*)(wl + LW_WIN), NTOK, C_GATE, DM}; pg8::RangeOrder S; S.init(NTOK, C_GATE, G, bx); S.i0 = i16; S.n = n16;
;                     pg8::EpiProj E{PROJ, NPROJ, (const float*)A.in[7] + (size_t)l * 6144, 1 << 20, ssq, 1.0f};
;                     pg8::gemm_phase<pg8::EpiProj, pg8::RangeOrder, true, true>(lds + RING_OFF, g, S, E); }
;                 if (do8) { pg8::Gemm g{(const bf16*)XB8, (const bf16*)(wl + LW_WIN + WIN8_OFF), NTOK, 6144, DM / 2}; pg8::RangeOrder S; S.init(NTOK, 6144, g8, c8); S.i0 = i8; S.n = n8;
;                     pg8::EpiGate8 E{(unsigned char*)(PROJ + C_GATE), NPROJ * 2, (const float*)A.in[7] + (size_t)l * 6144, ssq, 1.0f / 2048.0f};
;                     pg8::gemm_phase<pg8::EpiGate8, pg8::RangeOrder, true, true, true>(lds + RING_OFF, g, S, E); }
;                 if (part == 1) xcd_barrier(bar);
;                 if (part == 2 && (!std256 || bx >= 128)) { const int mb = std256 ? bx - 128 : bx, ms = std256 ? 128 : G;
;                     if ((ms & 3) == 0) pool_units(lds, PROJ, (const bf16*)(ws + WS_WPT) + (size_t)l * 4 * 192 * 192, Y + (size_t)NTOK * BRW, mb, ms, 512);
;                     else for (int u = mb; u < 512; u += ms) pool_units(lds, PROJ, (const bf16*)(ws + WS_WPT) + (size_t)l * 4 * 192 * 192, Y + (size_t)NTOK * BRW, u, 512, 512);
;                     gla_pre_items(lds, PROJ, (const float*)A.in[11] + (size_t)l * 16 * 384, (const float*)A.in[12] + l * 384, ws + WS_GPRE, mb, ms, 512); }
;             }
;             xcd_barrier(bar);
;             if (G > 96) { if (bx < 48) gla_scan_unit(lds, ws + WS_GPRE, GO, bx);
;                           else for (int u = bx - 48; u < 256; u += G - 48) att_unit(lds, PROJ, COS, SIN, (const float*)A.in[8] + l * 12, Y, u); }
;             else { for (int u = bx; u < 48; u += G) gla_scan_unit(lds, ws + WS_GPRE, GO, u);
	v_writelane_b32 v253, s7, 33
	s_add_u32 s6, s18, 0x4e00
	s_addc_u32 s7, s19, 0
	v_writelane_b32 v253, s6, 34
	s_nop 1
	v_writelane_b32 v253, s7, 35
	s_add_u32 s6, s18, 0x4f00
	s_addc_u32 s7, s19, 0
	v_writelane_b32 v253, s6, 36
	s_nop 1
	v_writelane_b32 v253, s7, 37
	s_add_u32 s6, s18, 0x5000
	s_addc_u32 s7, s19, 0
	v_writelane_b32 v253, s6, 38
	s_nop 1
	v_writelane_b32 v253, s7, 39
	s_add_u32 s6, s18, 0x5100
	s_addc_u32 s7, s19, 0
	v_writelane_b32 v253, s6, 40
	s_nop 1
	v_writelane_b32 v253, s7, 41
	s_add_u32 s6, s18, 0x5200
	s_addc_u32 s7, s19, 0
	v_writelane_b32 v253, s6, 42
	s_nop 1
	v_writelane_b32 v253, s7, 43
	s_add_u32 s6, s18, 0x5300
	s_addc_u32 s7, s19, 0
	v_writelane_b32 v253, s6, 44
	s_nop 1
	v_writelane_b32 v253, s7, 45
	s_add_u32 s6, s18, 0x7400
	s_addc_u32 s7, s19, 0
	v_writelane_b32 v253, s6, 46
	s_nop 1
	v_writelane_b32 v253, s7, 47
	s_add_u32 s6, s18, 0x7500
	s_addc_u32 s7, s19, 0
	v_writelane_b32 v253, s6, 48
	s_cmpk_eq_i32 s95, 0x100
	s_nop 0
	v_writelane_b32 v253, s7, 49
	s_cselect_b64 s[6:7], -1, 0
	s_add_u32 s72, s18, 0x2fe00000
	s_addc_u32 s73, s19, 0
	v_writelane_b32 v253, s6, 50
	s_cmp_lt_i32 s97, 64
	s_nop 0
	v_writelane_b32 v253, s7, 51
	s_cselect_b64 s[6:7], -1, 0
	v_writelane_b32 v253, s6, 52
	s_cmp_gt_i32 s97, 63
	s_nop 0
	v_writelane_b32 v253, s7, 53
	s_cselect_b64 s[6:7], -1, 0
	v_writelane_b32 v253, s6, 54
	s_cmpk_lt_i32 s97, 0x80
	s_nop 0
	v_writelane_b32 v253, s7, 55
	s_cselect_b64 s[6:7], -1, 0
	v_writelane_b32 v253, s6, 56
	s_sub_i32 s3, s97, 64
	s_nop 0
	v_writelane_b32 v253, s7, 57
	s_add_u32 s6, s18, 0x3b602400
	v_writelane_b32 v253, s3, 58
	s_addc_u32 s7, s19, 0
	v_writelane_b32 v253, s6, 59
	s_cmpk_gt_i32 s97, 0x7f
	s_nop 0
	v_writelane_b32 v253, s7, 60
	s_cselect_b64 s[6:7], -1, 0
	s_or_b64 s[0:1], s[6:7], s[0:1]
	v_writelane_b32 v253, s0, 61
	s_nop 1
	v_writelane_b32 v253, s1, 62
	s_and_b32 s0, s69, 3
	s_cmp_lg_u32 s0, 0
	s_cselect_b64 s[0:1], -1, 0
	v_writelane_b32 v253, s0, 63
	s_cmpk_lt_i32 s20, 0x200
	s_nop 0
	v_writelane_b32 v254, s1, 0
	s_cselect_b64 s[0:1], -1, 0
	v_writelane_b32 v254, s0, 1
	s_nop 1
	v_writelane_b32 v254, s1, 2
	s_add_u32 s0, s18, 0x46a00000
	s_addc_u32 s1, s19, 0
	v_writelane_b32 v254, s0, 3
	s_and_b32 s4, s20, 3
	s_nop 0
	v_writelane_b32 v254, s1, 4
	s_mul_i32 s0, s4, 0x12000
	s_add_u32 s0, s34, s0
	v_writelane_b32 v254, s0, 5
	v_writelane_b32 v254, s34, 6
	s_addc_u32 s0, s35, 0
	s_lshl_b32 s68, 2, s4
	v_writelane_b32 v254, s35, 7
	v_writelane_b32 v254, s0, 8
	s_lshl_b32 s1, s20, 4
	s_lshl_b32 s0, s69, 4
	s_add_u32 s22, s18, 0x4fc00000
	v_writelane_b32 v254, s0, 9
	s_addc_u32 s23, s19, 0
	s_lshl_b32 s0, s20, 6
	s_and_b32 s0, s0, 0x7c0
	v_writelane_b32 v254, s1, 10
	s_and_b32 s1, s1, 0xfffff800
	s_or_b32 s0, s1, s0
	s_ashr_i32 s1, s0, 31
	v_writelane_b32 v254, s0, 11
	s_bfe_u32 s3, s20, 0x20005
	s_mov_b32 s35, 0
	v_writelane_b32 v254, s1, 12
	s_mul_i32 s0, s3, 0x60
	v_writelane_b32 v254, s20, 13
	s_add_i32 s1, s0, 0x920
	v_writelane_b32 v254, s1, 14
	v_writelane_b32 v254, s0, 15
	s_bitset1_b32 s0, 11
	s_cmpk_lt_i32 s95, 0x61
	v_writelane_b32 v254, s0, 16
	s_cselect_b64 s[0:1], -1, 0
	s_cmpk_gt_i32 s95, 0x60
	v_writelane_b32 v254, s0, 17
	s_cselect_b64 s[6:7], -1, 0
	s_cmp_lt_i32 s97, 48
	v_writelane_b32 v254, s1, 18
	s_cselect_b64 s[0:1], -1, 0
	v_writelane_b32 v254, s0, 19
	s_cmpk_lt_i32 s97, 0x100
	s_nop 0
	v_writelane_b32 v254, s1, 20
	s_cselect_b64 s[0:1], -1, 0
	v_writelane_b32 v254, s0, 21
	s_nop 1
	v_writelane_b32 v254, s1, 22
	s_sub_i32 s0, s97, 48
	v_writelane_b32 v254, s0, 23
	s_cmpk_lt_i32 s97, 0x130
	s_mul_hi_i32 s0, s97, 0x55555556
	s_cselect_b64 s[8:9], -1, 0
	s_lshr_b32 s1, s0, 31
	s_add_i32 s10, s0, s1
	s_mul_i32 s0, s10, -3
	s_add_i32 s0, s0, s97
	v_writelane_b32 v254, s8, 24
	s_lshl_b32 s1, s0, 13
	s_add_i32 s1, s1, 0x8000
	v_writelane_b32 v254, s9, 25
	v_writelane_b32 v254, s1, 26
	s_sub_i32 s1, s95, 48
	v_writelane_b32 v254, s1, 27
	s_lshl_b32 s8, s10, 5
	s_mul_i32 s1, s10, 0x1c4000
	v_writelane_b32 v254, s8, 28
	s_mul_hi_i32 s8, s8, 0xe200
	s_add_u32 s14, s22, s1
	s_addc_u32 s15, s23, s8
	s_add_u32 s8, s14, 0xe000
	v_writelane_b32 v254, s14, 29
	s_addc_u32 s9, s15, 0
	s_lshl_b32 s1, s10, 9
	s_lshl_b32 s0, s0, 6
	v_writelane_b32 v254, s15, 30
	s_and_b32 s11, s1, 0xfffff800
	s_ashr_i32 s1, s0, 31
	v_writelane_b32 v254, s8, 31
	s_cmp_gt_i32 s97, 47
	s_nop 0
	v_writelane_b32 v254, s9, 32
	s_cselect_b64 s[8:9], -1, 0
	v_writelane_b32 v254, s8, 33
	s_mov_b64 s[14:15], s[6:7]
	s_add_i32 s6, s97, s95
	s_addk_i32 s6, 0xffa0
	v_writelane_b32 v254, s9, 34
	s_cmpk_lt_i32 s6, 0x100
	s_cselect_b32 s8, 2, 4
	v_writelane_b32 v254, s14, 35
	s_and_b64 s[6:7], s[14:15], exec
	s_cselect_b32 s6, s8, 0
	v_writelane_b32 v254, s15, 36
	v_writelane_b32 v254, s6, 37
	s_add_u32 s6, s18, 0x47600000
	v_writelane_b32 v254, s6, 38
	s_addc_u32 s6, s19, 0
	v_writelane_b32 v254, s6, 39
	s_lshl_b32 s14, s95, 5
	s_lshl_b32 s6, s5, 5
	s_cmp_lt_i32 s5, 0
	s_movk_i32 s7, 0xb1
	s_cselect_b32 s7, s7, 0xb0
;     __host__ __device__ bool next(int i, Unit& u) const {
;         const long L = (long)i * G + c; if (L >= nwg) return false;
;         int wgid = (int)L; { const int q = nwg / NXCD, r = nwg % NXCD, xcd = wgid % NXCD, off = wgid / NXCD; wgid = (xcd < r ? xcd * (q + 1) : r * (q + 1) + (xcd - r) * q) + off; }
;         const int nig = WGM * nN, gid = wgid / nig, fm = gid * WGM, gsz = (nM - fm) < WGM ? (nM - fm) : WGM;
;         u.pm = fm + ((wgid % nig) % gsz); u.pn = (wgid % nig) / gsz; u.seg = 0; return true;
; __global__ void __launch_bounds__(NWAVES * 64, 2) mega_fwd(Args A) {
;     ...
;             { const int rem1 = ((NTOK / 256) * (NWI / 256)) % G;
;               conv_until(A, lds, l * TL_LAYER + (kind == 0 ? TL_WIN : TL_LAYER), (rem1 != 0 && bx >= rem1) ? 3 : 0); }
	s_mul_i32 s7, s5, s7
	s_mul_i32 s5, s5, 33
	s_cselect_b32 s5, s5, s6
	s_add_i32 s7, s7, s2
	s_mul_hi_i32 s6, s7, 0x2e8ba2e9
	s_lshr_b32 s8, s6, 31
	s_ashr_i32 s6, s6, 6
	s_add_i32 s6, s6, s8
	s_mul_i32 s8, s6, 0x160
	s_sub_i32 s7, s7, s8
	s_bfe_u32 s8, s7, 0x3001c
	s_add_i32 s8, s7, s8
	s_and_b32 s9, s8, 0xfff8
	s_sub_i32 s7, s7, s9
	s_lshl_b32 s6, s6, 3
	s_sext_i32_i16 s8, s8
	s_sext_i32_i16 s7, s7
	s_add_i32 s16, s6, s7
	s_ashr_i32 s6, s8, 3
	v_writelane_b32 v254, s6, 40
	s_lshr_b32 s6, s8, 3
	s_bfe_i64 s[6:7], s[6:7], 0x100000
	s_lshl_b64 s[6:7], s[6:7], 20
	v_writelane_b32 v254, s6, 41
	s_ashr_i32 s17, s16, 31
	s_nop 0
	v_writelane_b32 v254, s7, 42
	s_mov_b32 s6, s16
	v_writelane_b32 v254, s6, 43
	s_nop 1
	v_writelane_b32 v254, s7, 44
	s_lshl_b64 s[6:7], s[16:17], 20
	s_add_u32 s6, s90, s6
	s_addc_u32 s7, s91, s7
	s_add_u32 s8, s6, 0x80000
	s_addc_u32 s9, s7, 0
	v_writelane_b32 v254, s8, 45
	s_nop 1
	v_writelane_b32 v254, s9, 46
	s_add_u32 s8, s6, 0x2000
	v_writelane_b32 v254, s6, 47
	s_addc_u32 s9, s7, 0
	s_add_i32 s2, s5, s2
	s_ashr_i32 s5, s2, 31
	s_lshr_b32 s5, s5, 26
	s_add_i32 s5, s2, s5
	v_writelane_b32 v254, s7, 48
	s_and_b32 s6, s5, 0xffc0
	s_sub_i32 s2, s2, s6
	s_bfe_i32 s6, s2, 0x80000
	s_bfe_u32 s6, s6, 0x3000c
	s_add_i32 s6, s2, s6
	s_and_b32 s7, s6, 0xf8
	s_sub_i32 s2, s2, s7
	s_ashr_i32 s5, s5, 6
	s_lshl_b32 s5, s5, 3
	s_sext_i32_i8 s2, s2
	s_add_i32 s5, s5, s2
	s_bfe_i32 s2, s6, 0x80000
	v_writelane_b32 v254, s8, 49
	s_sext_i32_i16 s2, s2
	s_ashr_i32 s6, s2, 3
	v_writelane_b32 v254, s9, 50
	s_lshr_b32 s2, s2, 3
	v_writelane_b32 v254, s6, 51
	s_bfe_i64 s[6:7], s[2:3], 0x100000
	v_writelane_b32 v254, s6, 52
	s_mul_hi_i32 s2, s5, 0x60000
	s_nop 0
	v_writelane_b32 v254, s7, 53
	v_writelane_b32 v254, s5, 54
	s_mul_i32 s5, s5, 0x60000
	s_add_u32 s6, s12, s5
	s_addc_u32 s7, s13, s2
	s_add_u32 s8, s6, 0x30000
	s_addc_u32 s9, s7, 0
	v_writelane_b32 v254, s8, 55
	s_nop 1
	v_writelane_b32 v254, s9, 56
	s_add_u32 s8, s6, 0x2000
	v_writelane_b32 v254, s6, 57
	s_addc_u32 s9, s7, 0
	s_abs_i32 s2, s95
	v_cvt_f32_u32_e32 v1, s2
	v_writelane_b32 v254, s7, 58
	s_sub_i32 s5, 0, s2
	v_writelane_b32 v254, s8, 59
	v_rcp_iflag_f32_e32 v1, v1
	s_nop 0
	v_writelane_b32 v254, s9, 60
	v_mul_f32_e32 v1, 0x4f7ffffe, v1
	v_cvt_u32_f32_e32 v1, v1
	s_nop 0
	v_readfirstlane_b32 s6, v1
	s_mul_i32 s5, s5, s6
	s_mul_hi_u32 s5, s6, s5
	s_add_i32 s6, s6, s5
	s_mul_hi_u32 s5, s6, 0x580
	s_mul_i32 s5, s5, s2
	s_sub_i32 s5, 0x580, s5
	s_sub_i32 s6, s5, s2
	s_cmp_ge_u32 s5, s2
	s_cselect_b32 s5, s6, s5
	s_sub_i32 s6, s5, s2
	s_cmp_ge_u32 s5, s2
	s_cselect_b32 s2, s6, s5
	s_cmp_lg_u32 s2, 0
	s_cselect_b64 s[6:7], -1, 0
	s_and_b32 s5, s97, 7
	s_cmp_ge_u32 s5, 4
	s_cselect_b64 s[8:9], -1, 0
	s_and_b64 s[6:7], s[6:7], s[8:9]
	s_mul_i32 s2, s4, 0xc0
	v_writelane_b32 v254, s6, 61
	s_and_b64 s[4:5], s[6:7], exec
	s_cselect_b32 s4, 4, 0
	v_writelane_b32 v254, s7, 62
	v_writelane_b32 v255, s2, 0
	s_lshl_b32 s2, s2, 1
	v_writelane_b32 v254, s4, 63
	s_add_u32 s4, s88, s2
	s_addc_u32 s5, s89, 0
	v_writelane_b32 v255, s4, 1
	s_and_b32 s2, s10, 3
	s_mulk_i32 s2, 0x300
	v_writelane_b32 v255, s5, 2
	s_mul_i32 s4, s11, 0xc00
	s_lshl_b32 s5, s97, 6
	s_or_b32 s2, s4, s2
	s_lshl_b64 s[0:1], s[0:1], 2
	v_writelane_b32 v255, s5, 3
	s_lshl_b32 s5, s95, 6
	s_mul_hi_i32 s4, s11, 0xc00
	s_add_u32 s0, s2, s0
	s_addc_u32 s1, s4, s1
	s_add_u32 s0, s18, s0
	v_writelane_b32 v255, s5, 4
	s_addc_u32 s1, s19, s1
	v_writelane_b32 v255, s0, 5
	s_mul_i32 s2, s95, 0x18000
	s_add_i32 s93, 0, 0x20180
	v_writelane_b32 v255, s1, 6
	s_mul_i32 s0, s3, 0xc0
	s_mul_hi_i32 s3, s14, 0xc00
	v_writelane_b32 v255, s2, 7
	s_lshl_b32 s1, s97, 9
	s_lshl_b32 s0, s0, 1
	v_writelane_b32 v255, s3, 8
	s_mul_i32 s2, s95, 0xa8000
	v_writelane_b32 v255, s14, 9
	s_mul_hi_i32 s3, s14, 0x5400
	v_writelane_b32 v255, s2, 10
	s_add_i32 s60, 0, 0x20184
	v_mov_b32_e32 v1, 0x358637bd
	v_writelane_b32 v255, s3, 11
	v_writelane_b32 v255, s1, 12
	s_lshl_b32 s1, s95, 11
	v_writelane_b32 v255, s1, 13
	s_lshl_b32 s1, s95, 4
	v_writelane_b32 v255, s1, 14
	s_lshl_b32 s1, s95, 10
	v_writelane_b32 v255, s1, 15
	s_lshl_b32 s1, s95, 9
	v_writelane_b32 v255, s1, 16
	s_add_i32 s1, 0, 0x20160
	v_writelane_b32 v255, s1, 17
	s_add_i32 s1, 0, 0x20164
	v_writelane_b32 v255, s1, 18
	s_add_i32 s1, 0, 0x2d00
	v_writelane_b32 v255, s1, 19
	v_writelane_b32 v255, s0, 20
	s_add_i32 s64, 0, 0x12600
	s_nop 0
	v_writelane_b32 v255, s1, 21
	s_add_i32 s0, 0, 0xf000
	v_writelane_b32 v255, s0, 22
	s_add_i32 s0, 0, 0x8800
	v_writelane_b32 v255, s0, 23
	v_writelane_b32 v255, s90, 24
	s_nop 1
	v_writelane_b32 v255, s91, 25
	v_writelane_b32 v255, s69, 26
	v_writelane_b32 v255, s88, 27
	s_nop 1
	v_writelane_b32 v255, s89, 28
	v_writelane_b32 v255, s21, 29
	v_writelane_b32 v255, s22, 30
	v_writelane_b32 v255, s23, 31
	v_writelane_b32 v255, s93, 32
	v_writelane_b32 v255, s60, 33
	v_writelane_b32 v255, s92, 34
	s_nop 1
	v_writelane_b32 v255, s93, 35
	s_branch .LBB0_287
